# fox early-exit vote: its decay value is read from LDS at the top of the step, not right in front of the step barrier
# speedup vs baseline: 1.0122x; 1.0016x over previous
; template<int MODE,int THRL> __device__ __forceinline__ void attn_unit(int b,int h,int qb,const bf16*Q,const bf16*__restrict__ K,const bf16*__restrict__ V,bf16*O,char*shm,const float*__restrict__ cs2,const float*__restrict__ relb,float kmx){
;     ...
;     if constexpr(MODE==0){ if(t>=3){ const float Bn=-*(const __attribute__((address_space(3))) float*)(shm3+LDS_X+(64*(NT-3-t)+63)*4); const bool c_=(ub+Bn-mhat)<-160.f; const bool a_=__all(c_); if(lane==0)votes[wid]=a_?1u:0u; } }
.LBB0_257:
	s_add_i32 s2, s56, 0x2000
	s_cmpk_lg_i32 s56, 0x4000
	s_cselect_b32 s2, s2, 0
	s_waitcnt lgkmcnt(1)
	s_add_i32 s26, s28, 0x1c4fc
	v_mov_b32_e32 v250, s26
	ds_read_b32 v250, v250
	v_xor_b32_e32 v1, 0x80000000, v0
	v_and_b32_e32 v37, 0xffff0000, v1
	v_sub_f32_e64 v0, -v0, v37
	v_and_b32_e32 v37, 0xffff0000, v0
	v_sub_f32_e32 v0, v0, v37
	v_or_b32_sdwa v1, v37, v1 dst_sel:DWORD dst_unused:UNUSED_PAD src0_sel:DWORD src1_sel:WORD_1
	v_or_b32_sdwa v37, v0, v223 dst_sel:DWORD dst_unused:UNUSED_PAD src0_sel:WORD_1 src1_sel:DWORD
	v_cndmask_b32_e64 v0, 0, v1, s[42:43]
	v_cndmask_b32_e64 v1, 0, v37, s[42:43]
	s_waitcnt lgkmcnt(0)
	v_xor_b32_e32 v37, 0x80000000, v36
	v_and_b32_e32 v38, 0xffff0000, v37
	v_sub_f32_e64 v36, -v36, v38
	v_and_b32_e32 v38, 0xffff0000, v36
	v_sub_f32_e32 v36, v36, v38
	v_or_b32_sdwa v37, v38, v37 dst_sel:DWORD dst_unused:UNUSED_PAD src0_sel:DWORD src1_sel:WORD_1
	v_or_b32_sdwa v53, v36, v223 dst_sel:DWORD dst_unused:UNUSED_PAD src0_sel:WORD_1 src1_sel:DWORD
	v_cndmask_b32_e64 v52, 0, v37, s[42:43]
	v_cndmask_b32_e64 v53, 0, v53, s[42:43]
	v_mov_b32_e32 v54, v2
	v_mov_b32_e32 v55, v3
	v_mfma_f32_32x32x16_bf16 v[36:51], v[0:3], v[132:135], 0
	v_add_u32_e32 v0, s52, v230
	v_mfma_f32_32x32x16_bf16 v[52:67], v[52:55], v[132:135], 0
	ds_read_b64_tr_b16 v[136:137], v0 offset:24576
	ds_read_b64_tr_b16 v[138:139], v0 offset:25088
	v_mfma_f32_32x32x16_bf16 v[36:51], v[168:171], v[112:115], v[36:51]
	v_add_f32_e32 v1, v84, v85
	v_add_f32_e32 v1, v86, v1
	v_add_f32_e32 v1, v87, v1
	v_add_f32_e32 v1, v88, v1
	v_add_f32_e32 v1, v89, v1
	v_cvt_pk_bf16_f32 v128, v84, v85
	v_cvt_pk_bf16_f32 v129, v86, v87
	ds_read_b64_tr_b16 v[84:85], v0 offset:28672
	ds_read_b64_tr_b16 v[86:87], v0 offset:29184
	v_mfma_f32_32x32x16_bf16 v[52:67], v[164:167], v[112:115], v[52:67]
	v_add_f32_e32 v1, v90, v1
	v_add_f32_e32 v1, v91, v1
	v_add_f32_e32 v1, v92, v1
	v_add_f32_e32 v1, v93, v1
	v_cvt_pk_bf16_f32 v130, v88, v89
	v_cvt_pk_bf16_f32 v131, v90, v91
	ds_read_b64_tr_b16 v[88:89], v0 offset:25600
	ds_read_b64_tr_b16 v[90:91], v0 offset:26112
	v_mfma_f32_32x32x16_bf16 v[36:51], v[160:163], v[108:111], v[36:51]
	v_add_f32_e32 v1, v94, v1
	v_add_f32_e32 v1, v95, v1
	v_add_f32_e32 v1, v96, v1
	v_add_f32_e32 v1, v97, v1
	v_cvt_pk_bf16_f32 v124, v92, v93
	v_cvt_pk_bf16_f32 v125, v94, v95
	ds_read_b64_tr_b16 v[92:93], v0 offset:29696
	ds_read_b64_tr_b16 v[94:95], v0 offset:30208
	v_mfma_f32_32x32x16_bf16 v[52:67], v[156:159], v[108:111], v[52:67]
	v_add_f32_e32 v1, v98, v1
	v_add_f32_e32 v1, v99, v1
	v_add_f32_e32 v1, v68, v1
	v_add_f32_e32 v1, v69, v1
	v_cvt_pk_bf16_f32 v126, v96, v97
	v_cvt_pk_bf16_f32 v127, v98, v99
	ds_read_b64_tr_b16 v[96:97], v0 offset:26624
	ds_read_b64_tr_b16 v[98:99], v0 offset:27136
	v_mfma_f32_32x32x16_bf16 v[36:51], v[152:155], v[104:107], v[36:51]
	v_add_f32_e32 v1, v70, v1
	v_add_f32_e32 v1, v71, v1
	v_add_f32_e32 v1, v72, v1
	v_add_f32_e32 v1, v73, v1
	v_cvt_pk_bf16_f32 v120, v68, v69
	v_cvt_pk_bf16_f32 v121, v70, v71
	ds_read_b64_tr_b16 v[68:69], v0 offset:30720
	ds_read_b64_tr_b16 v[70:71], v0 offset:31232
	v_mfma_f32_32x32x16_bf16 v[52:67], v[148:151], v[104:107], v[52:67]
	v_add_f32_e32 v1, v74, v1
	v_add_f32_e32 v1, v75, v1
	v_add_f32_e32 v1, v76, v1
	v_add_f32_e32 v1, v77, v1
	v_cvt_pk_bf16_f32 v122, v72, v73
	v_cvt_pk_bf16_f32 v123, v74, v75
	ds_read_b64_tr_b16 v[72:73], v0 offset:27648
	ds_read_b64_tr_b16 v[74:75], v0 offset:28160
	v_mfma_f32_32x32x16_bf16 v[36:51], v[144:147], v[100:103], v[36:51]
	v_add_f32_e32 v1, v78, v1
	v_add_f32_e32 v1, v79, v1
	v_add_f32_e32 v1, v80, v1
	v_add_f32_e32 v1, v81, v1
	v_cvt_pk_bf16_f32 v116, v76, v77
	v_cvt_pk_bf16_f32 v117, v78, v79
	ds_read_b64_tr_b16 v[76:77], v0 offset:31744
	ds_read_b64_tr_b16 v[78:79], v0 offset:32256
	v_mfma_f32_32x32x16_bf16 v[52:67], v[140:143], v[100:103], v[52:67]
	v_add_f32_e32 v0, v82, v1
	v_add_f32_e32 v0, v83, v0
	v_add_f32_e32 v0, 0, v0
	v_cvt_pk_bf16_f32 v118, v80, v81
	v_cvt_pk_bf16_f32 v119, v82, v83
	s_add_i32 s26, s56, s6
	s_mov_b32 s52, m0
	s_mov_b32 m0, s26
	s_nop 0
	global_load_lds_dwordx4 v[176:177], off
	s_mov_b32 m0, s52
	s_add_i32 s26, s2, s5
	s_add_i32 s53, s33, 2
	s_mov_b32 s33, m0
	s_mov_b32 m0, s26
	s_nop 0
	global_load_lds_dwordx4 v[178:179], off
	s_mov_b32 m0, s33
	s_cmp_lt_i32 s53, 0
	s_cbranch_scc1 .LBB0_259
; __device__ __forceinline__ void cmask(f32x16&p0,f32x16&p1,int jb,int qrel,int hi){
;   const float NEG=-INFINITY; int kb=64*jb+4*hi;
;   #pragma unroll
;   for(int r=0;r<16;++r){int kv=kb+(r&3)+8*(r>>2); if(kv>qrel)p0[r]=NEG; if(kv+32>qrel)p1[r]=NEG;}
; }
	v_add_u32_e32 v80, 0xffffffa5, v184
	v_add_u32_e32 v1, 0xffffff85, v184
	v_cmp_le_i32_e32 vcc, v80, v211
	s_nop 1
	v_cndmask_b32_e32 v52, v217, v52, vcc
	v_cmp_lt_i32_e32 vcc, v1, v211
	s_nop 1
	v_cndmask_b32_e32 v37, v217, v37, vcc
	v_cmp_le_i32_e32 vcc, v1, v211
	v_add_u32_e32 v1, 0xffffffa6, v184
	s_nop 0
	v_cndmask_b32_e32 v36, v217, v36, vcc
	v_cmp_le_i32_e32 vcc, v1, v211
	v_add_u32_e32 v1, 0xffffff87, v184
	s_nop 0
	v_cndmask_b32_e32 v53, v217, v53, vcc
	v_cmp_le_i32_e32 vcc, v1, v211
	v_add_u32_e32 v1, 0xffffffa7, v184
	s_nop 0
	v_cndmask_b32_e32 v38, v217, v38, vcc
	v_cmp_le_i32_e32 vcc, v1, v211
	v_add_u32_e32 v1, 0xffffff88, v184
	s_nop 0
	v_cndmask_b32_e32 v54, v217, v54, vcc
	v_cmp_le_i32_e32 vcc, v1, v211
	v_add_u32_e32 v1, 0xffffffa8, v184
	s_nop 0
	v_cndmask_b32_e32 v39, v217, v39, vcc
	v_cmp_le_i32_e32 vcc, v1, v211
	v_add_u32_e32 v1, 0xffffff8d, v184
	s_nop 0
	v_cndmask_b32_e32 v55, v217, v55, vcc
	v_cmp_le_i32_e32 vcc, v1, v211
	v_add_u32_e32 v1, 0xffffffad, v184
	s_nop 0
	v_cndmask_b32_e32 v40, v217, v40, vcc
	v_cmp_le_i32_e32 vcc, v1, v211
	v_add_u32_e32 v1, 0xffffff8e, v184
	s_nop 0
	v_cndmask_b32_e32 v56, v217, v56, vcc
	v_cmp_le_i32_e32 vcc, v1, v211
	v_add_u32_e32 v1, 0xffffffae, v184
	s_nop 0
	v_cndmask_b32_e32 v41, v217, v41, vcc
	v_cmp_le_i32_e32 vcc, v1, v211
	v_add_u32_e32 v1, 0xffffff8f, v184
	s_nop 0
	v_cndmask_b32_e32 v57, v217, v57, vcc
	v_cmp_le_i32_e32 vcc, v1, v211
	v_add_u32_e32 v1, 0xffffffaf, v184
	s_nop 0
	v_cndmask_b32_e32 v42, v217, v42, vcc
	v_cmp_le_i32_e32 vcc, v1, v211
	v_add_u32_e32 v1, 0xffffff90, v184
	s_nop 0
	v_cndmask_b32_e32 v58, v217, v58, vcc
	v_cmp_le_i32_e32 vcc, v1, v211
	v_add_u32_e32 v1, 0xffffffb0, v184
	s_nop 0
	v_cndmask_b32_e32 v43, v217, v43, vcc
	v_cmp_le_i32_e32 vcc, v1, v211
	v_add_u32_e32 v1, 0xffffff95, v184
	s_nop 0
	v_cndmask_b32_e32 v59, v217, v59, vcc
	v_cmp_le_i32_e32 vcc, v1, v211
	v_add_u32_e32 v1, 0xffffffb5, v184
	s_nop 0
	v_cndmask_b32_e32 v44, v217, v44, vcc
	v_cmp_le_i32_e32 vcc, v1, v211
	v_add_u32_e32 v1, 0xffffff96, v184
	s_nop 0
	v_cndmask_b32_e32 v60, v217, v60, vcc
	v_cmp_le_i32_e32 vcc, v1, v211
	v_add_u32_e32 v1, 0xffffffb6, v184
	s_nop 0
	v_cndmask_b32_e32 v45, v217, v45, vcc
	v_cmp_le_i32_e32 vcc, v1, v211
	v_add_u32_e32 v1, 0xffffff97, v184
	s_nop 0
	v_cndmask_b32_e32 v61, v217, v61, vcc
	v_cmp_le_i32_e32 vcc, v1, v211
	v_add_u32_e32 v1, 0xffffffb7, v184
	s_nop 0
	v_cndmask_b32_e32 v46, v217, v46, vcc
	v_cmp_le_i32_e32 vcc, v1, v211
	v_add_u32_e32 v1, 0xffffff98, v184
	s_nop 0
	v_cndmask_b32_e32 v62, v217, v62, vcc
	v_cmp_le_i32_e32 vcc, v1, v211
	v_add_u32_e32 v1, 0xffffffb8, v184
	s_nop 0
	v_cndmask_b32_e32 v47, v217, v47, vcc
	v_cmp_le_i32_e32 vcc, v1, v211
	v_add_u32_e32 v1, 0xffffff9d, v184
	s_nop 0
	v_cndmask_b32_e32 v63, v217, v63, vcc
	v_cmp_le_i32_e32 vcc, v1, v211
	v_add_u32_e32 v1, 0xffffffbd, v184
	s_nop 0
	v_cndmask_b32_e32 v48, v217, v48, vcc
	v_cmp_le_i32_e32 vcc, v1, v211
	v_add_u32_e32 v1, 0xffffff9e, v184
	s_nop 0
	v_cndmask_b32_e32 v64, v217, v64, vcc
	v_cmp_le_i32_e32 vcc, v1, v211
	v_add_u32_e32 v1, 0xffffffbe, v184
	s_nop 0
	v_cndmask_b32_e32 v49, v217, v49, vcc
	v_cmp_le_i32_e32 vcc, v1, v211
	v_add_u32_e32 v1, 0xffffff9f, v184
	s_nop 0
	v_cndmask_b32_e32 v65, v217, v65, vcc
	v_cmp_le_i32_e32 vcc, v1, v211
	v_add_u32_e32 v1, 0xffffffbf, v184
	s_nop 0
	v_cndmask_b32_e32 v50, v217, v50, vcc
	v_cmp_le_i32_e32 vcc, v1, v211
	v_add_u32_e32 v1, 0xffffffa0, v184
	s_nop 0
	v_cndmask_b32_e32 v66, v217, v66, vcc
	v_cmp_le_i32_e32 vcc, v1, v211
	v_subrev_u32_e32 v1, 64, v184
	s_nop 0
	v_cndmask_b32_e32 v51, v217, v51, vcc
	v_cmp_le_i32_e32 vcc, v1, v211
	s_nop 1
	v_cndmask_b32_e32 v67, v217, v67, vcc

; template<int MODE,int THRL> __device__ __forceinline__ void attn_unit(int b,int h,int qb,const bf16*Q,const bf16*__restrict__ K,const bf16*__restrict__ V,bf16*O,char*shm,const float*__restrict__ cs2,const float*__restrict__ relb,float kmx){
;     ...
;     if constexpr(MODE==0){ if(t>=3){ const float Bn=-*(const __attribute__((address_space(3))) float*)(shm3+LDS_X+(64*(NT-3-t)+63)*4); const bool c_=(ub+Bn-mhat)<-160.f; const bool a_=__all(c_); if(lane==0)votes[wid]=a_?1u:0u; } }
.LBB0_260:
	s_add_i32 s52, s51, -5
	s_waitcnt lgkmcnt(14)
	v_mfma_f32_32x32x16_bf16 v[20:35], v[128:131], v[136:139], v[20:35]
	v_exp_f32_e32 v36, v36
	v_exp_f32_e32 v37, v37
	v_exp_f32_e32 v38, v38
	v_exp_f32_e32 v39, v39
	s_waitcnt lgkmcnt(12)
	v_mfma_f32_32x32x16_bf16 v[4:19], v[128:131], v[84:87], v[4:19]
	v_exp_f32_e32 v40, v40
	v_exp_f32_e32 v41, v41
	v_exp_f32_e32 v42, v42
	v_exp_f32_e32 v43, v43
	v_add_u32_e32 v0, s2, v231
	ds_read_b128 v[164:167], v0
	ds_read_b128 v[160:163], v0 offset:512
	s_waitcnt lgkmcnt(12)
	v_mfma_f32_32x32x16_bf16 v[20:35], v[124:127], v[88:91], v[20:35]
	v_exp_f32_e32 v44, v44
	v_exp_f32_e32 v45, v45
	v_exp_f32_e32 v46, v46
	v_exp_f32_e32 v47, v47
	ds_read_b128 v[156:159], v0 offset:2048
	ds_read_b128 v[152:155], v0 offset:2560
	s_waitcnt lgkmcnt(12)
	v_mfma_f32_32x32x16_bf16 v[4:19], v[124:127], v[92:95], v[4:19]
	v_exp_f32_e32 v48, v48
	v_exp_f32_e32 v49, v49
	v_exp_f32_e32 v50, v50
	v_exp_f32_e32 v51, v51
	ds_read_b128 v[148:151], v0 offset:4096
	ds_read_b128 v[144:147], v0 offset:4608
	s_waitcnt lgkmcnt(12)
	v_mfma_f32_32x32x16_bf16 v[20:35], v[120:123], v[96:99], v[20:35]
	v_exp_f32_e32 v52, v52
	v_exp_f32_e32 v53, v53
	v_exp_f32_e32 v54, v54
	v_exp_f32_e32 v55, v55
	ds_read_b128 v[140:143], v0 offset:6144
	ds_read_b128 v[136:139], v0 offset:6656
	s_waitcnt lgkmcnt(12)
	v_mfma_f32_32x32x16_bf16 v[4:19], v[120:123], v[68:71], v[4:19]
	v_exp_f32_e32 v56, v56
	v_exp_f32_e32 v57, v57
	v_exp_f32_e32 v58, v58
	v_exp_f32_e32 v59, v59
	s_waitcnt lgkmcnt(10)
	v_mfma_f32_32x32x16_bf16 v[20:35], v[116:119], v[72:75], v[20:35]
	v_exp_f32_e32 v60, v60
	v_exp_f32_e32 v61, v61
	v_exp_f32_e32 v62, v62
	v_exp_f32_e32 v63, v63
	s_waitcnt lgkmcnt(8)
	v_mfma_f32_32x32x16_bf16 v[4:19], v[116:119], v[76:79], v[4:19]
	v_exp_f32_e32 v64, v64
	v_exp_f32_e32 v65, v65
	v_exp_f32_e32 v66, v66
	v_exp_f32_e32 v67, v67
	v_add_u32_e32 v0, 0x1c400, v180
	v_add_u32_e32 v1, 0x1c480, v180
	ds_read_b32 v180, v0
	ds_read_b32 v181, v1
	s_cmp_gt_u32 s52, 2
	s_cselect_b64 s[60:61], -1, 0
	s_cmp_lt_u32 s52, 3
	s_cselect_b64 s[58:59], -1, 0
	s_and_b64 vcc, exec, s[58:59]
	s_cbranch_vccnz .LBB0_264
	s_mov_b32 s26, 0xc2800000
	s_mov_b64 s[62:63], exec
	s_waitcnt lgkmcnt(2)
	v_sub_f32_e32 v0, v183, v250
	v_sub_f32_e32 v0, v0, v232
	v_cmp_gt_f32_e32 vcc, s26, v0
	s_and_saveexec_b64 s[64:65], s[44:45]
	s_cmp_eq_u64 vcc, s[62:63]
	s_cselect_b64 s[62:63], -1, 0
	v_cndmask_b32_e64 v0, 0, 1, s[62:63]
	v_mov_b32_e32 v1, s22
	ds_write_b32 v1, v0
	s_or_b64 exec, exec, s[64:65]
